# attention softmax row-max all-reduce: ds_bpermute LDS round trips replaced by v_permlane16_swap/v_permlane32_swap (4 update sites), on top of v43
# speedup vs baseline: 1.0047x; 1.0047x over previous
; #define LAS __attribute__((address_space(3)))
; __device__ __forceinline__ void attn_pair_update(QTile& t0, const int mq0, QTile& t1, const int mq1, int mk0, unsigned VSa, LAS unsigned char* KS, int lane) {
;     ...
;         const bf16x8 a0 = *(const LAS bf16x8*)(KS + ((fr)*HP + 32 * kk + 8 * fq) * 2);
;         const bf16x8 a1 = *(const LAS bf16x8*)(KS + ((16 + fr) * HP + 32 * kk + 8 * fq) * 2);
;         s00 = __builtin_amdgcn_mfma_f32_16x16x32_bf16(a0, t0.q[kk], s00, 0, 0, 0);
;         s01 = __builtin_amdgcn_mfma_f32_16x16x32_bf16(a1, t0.q[kk], s01, 0, 0, 0);
;         s10 = __builtin_amdgcn_mfma_f32_16x16x32_bf16(a0, t1.q[kk], s10, 0, 0, 0);
;         s11 = __builtin_amdgcn_mfma_f32_16x16x32_bf16(a1, t1.q[kk], s11, 0, 0, 0);
;     }
;     const float NEG = -__builtin_inff();
;     float mx0 = NEG, mx1 = NEG;
; #pragma unroll
;     for (int j = 0; j < 4; ++j) {
;         const int mk = mk0 + 4 * fq + j, jd0 = mq0 - mk, jd1 = mq1 - mk;
;         const bool kv0 = (mk >= 0), kv1 = (mk + 16 >= 0);
;         if (!((jd0 >= 0) && (jd0 <= 128) && kv0)) s00[j] = NEG;
;         if (!((jd0 - 16 >= 0) && (jd0 - 16 <= 128) && kv1)) s01[j] = NEG;
;         if (!((jd1 >= 0) && (jd1 <= 128) && kv0)) s10[j] = NEG;
;         if (!((jd1 - 16 >= 0) && (jd1 - 16 <= 128) && kv1)) s11[j] = NEG;
;         mx0 = fmaxf(mx0, fmaxf(s00[j], s01[j])); mx1 = fmaxf(mx1, fmaxf(s10[j], s11[j]));
;     }
;     { const float a = __shfl_xor(mx0, 16), b = __shfl_xor(mx1, 16); mx0 = fmaxf(mx0, a); mx1 = fmaxf(mx1, b); }
;     { const float a = __shfl_xor(mx0, 32), b = __shfl_xor(mx1, 32); mx0 = fmaxf(mx0, a); mx1 = fmaxf(mx1, b); }
.LBB0_782:
	v_add3_u32 v2, s17, v198, v199
	ds_read_b128 v[120:123], v2
	ds_read_b128 v[124:127], v2 offset:64
	ds_read_b128 v[132:135], v2 offset:4352
	ds_read_b128 v[136:139], v2 offset:4416
	v_add_u32_e32 v3, s13, v117
	v_cmp_lt_i32_e32 vcc, -1, v118
	s_waitcnt lgkmcnt(3)
	v_mfma_f32_16x16x32_bf16 v[128:131], v[120:123], v[8:11], 0
	v_cmp_lt_i32_e64 s[4:5], s52, v118
	v_add_u32_e32 v110, 0x90, v3
	s_waitcnt lgkmcnt(1)
	v_mfma_f32_16x16x32_bf16 v[140:143], v[132:135], v[8:11], 0
	v_mfma_f32_16x16x32_bf16 v[120:123], v[120:123], v[36:39], 0
	v_mfma_f32_16x16x32_bf16 v[132:135], v[132:135], v[36:39], 0
	v_mfma_f32_16x16x32_bf16 v[128:131], v[124:127], v[16:19], v[128:131]
	s_waitcnt lgkmcnt(0)
	v_mfma_f32_16x16x32_bf16 v[140:143], v[136:139], v[16:19], v[140:143]
	v_mfma_f32_16x16x32_bf16 v[120:123], v[124:127], v[44:47], v[120:123]
	v_mfma_f32_16x16x32_bf16 v[124:127], v[136:139], v[44:47], v[132:135]
	s_nop 2
	ds_read_b128 v[132:135], v2 offset:128
	ds_read_b128 v[136:139], v2 offset:192
	ds_read_b128 v[144:147], v2 offset:4480
	ds_read_b128 v[148:151], v2 offset:4544
	v_add_u32_e32 v2, 0x80, v3
	s_waitcnt lgkmcnt(3)
	v_mfma_f32_16x16x32_bf16 v[128:131], v[132:135], v[20:23], v[128:131]
	v_cmp_gt_u32_e64 s[6:7], s53, v2
	v_mov_b32_e32 v2, s55
	s_and_b64 s[8:9], vcc, s[6:7]
	s_waitcnt lgkmcnt(1)
	v_mfma_f32_16x16x32_bf16 v[140:143], v[144:147], v[20:23], v[140:143]
	v_mfma_f32_16x16x32_bf16 v[128:131], v[136:139], v[24:27], v[128:131]
	v_mfma_f32_16x16x32_bf16 v[120:123], v[132:135], v[52:55], v[120:123]
	v_mfma_f32_16x16x32_bf16 v[124:127], v[144:147], v[52:55], v[124:127]
	s_nop 5
	v_cndmask_b32_e64 v111, v2, v128, s[8:9]
	v_add_u32_e32 v2, 0x70, v3
	v_cmp_gt_u32_e64 s[8:9], s53, v2
	s_waitcnt lgkmcnt(0)
	v_mfma_f32_16x16x32_bf16 v[132:135], v[148:151], v[24:27], v[140:143]
	v_mov_b32_e32 v2, s55
	s_and_b64 s[8:9], s[4:5], s[8:9]
	v_add_u32_e32 v128, 0x6f, v3
	v_mfma_f32_16x16x32_bf16 v[120:123], v[136:139], v[56:59], v[120:123]
	v_mfma_f32_16x16x32_bf16 v[124:127], v[148:151], v[56:59], v[124:127]
	s_nop 2
	v_cndmask_b32_e64 v113, v2, v132, s[8:9]
	v_cmp_gt_u32_e64 s[8:9], s53, v110
	s_and_b64 vcc, vcc, s[8:9]
	s_nop 0
	v_cndmask_b32_e32 v114, v2, v120, vcc
	s_and_b64 vcc, s[4:5], s[6:7]
	v_cndmask_b32_e32 v115, v2, v124, vcc
	v_max_f32_e32 v2, v113, v113
	v_max_f32_e32 v110, v111, v111
	v_max_f32_e32 v2, v110, v2
	v_max_f32_e32 v110, v115, v115
	v_max_f32_e32 v120, v114, v114
	v_max_f32_e32 v110, v120, v110
	v_add_u32_e32 v120, 0x7f, v3
	v_cmp_lt_i32_e32 vcc, -2, v118
	v_cmp_gt_u32_e64 s[6:7], s53, v120
	s_and_b64 s[8:9], vcc, s[6:7]
	v_cmp_lt_i32_e64 s[4:5], s56, v118
	v_cndmask_b32_e64 v120, v214, v129, s[8:9]
	v_cmp_gt_u32_e64 s[8:9], s53, v128
	v_add_u32_e32 v124, 0x8f, v3
	s_and_b64 s[8:9], s[4:5], s[8:9]
	v_cndmask_b32_e64 v128, v214, v133, s[8:9]
	v_cmp_gt_u32_e64 s[8:9], s53, v124
	s_and_b64 vcc, vcc, s[8:9]
	v_cndmask_b32_e32 v124, v214, v121, vcc
	s_and_b64 vcc, s[4:5], s[6:7]
	v_cndmask_b32_e32 v129, v214, v125, vcc
	v_max_f32_e32 v121, v128, v128
	v_max_f32_e32 v125, v120, v120
	v_max_f32_e32 v121, v125, v121
	v_max3_f32 v2, v2, s55, v121
	v_max_f32_e32 v121, v129, v129
	v_max_f32_e32 v125, v124, v124
	v_max_f32_e32 v121, v125, v121
	v_max3_f32 v110, v110, s55, v121
	v_add_u32_e32 v121, 0x7e, v3
	v_cmp_lt_i32_e32 vcc, -3, v118
	v_cmp_gt_u32_e64 s[6:7], s53, v121
	s_and_b64 s[8:9], vcc, s[6:7]
	v_add_u32_e32 v121, 0x6e, v3
	v_cmp_lt_i32_e64 s[4:5], s57, v118
	v_cndmask_b32_e64 v130, v214, v130, s[8:9]
	v_cmp_gt_u32_e64 s[8:9], s53, v121
	v_add_u32_e32 v125, 0x8e, v3
	s_and_b64 s[8:9], s[4:5], s[8:9]
	v_cndmask_b32_e64 v132, v214, v134, s[8:9]
	v_cmp_gt_u32_e64 s[8:9], s53, v125
	s_and_b64 vcc, vcc, s[8:9]
	v_cndmask_b32_e32 v122, v214, v122, vcc
	s_and_b64 vcc, s[4:5], s[6:7]
	v_cndmask_b32_e32 v133, v214, v126, vcc
	v_max_f32_e32 v121, v132, v132
	v_max_f32_e32 v125, v130, v130
	v_max_f32_e32 v121, v125, v121
	v_max_f32_e32 v125, v133, v133
	v_max_f32_e32 v126, v122, v122
	v_max_f32_e32 v125, v126, v125
	v_add_u32_e32 v126, 0x7d, v3
	v_cmp_lt_i32_e32 vcc, -4, v118
	v_cmp_gt_u32_e64 s[6:7], s53, v126
	v_add_u32_e32 v134, 0x8d, v3
	s_and_b64 s[8:9], vcc, s[6:7]
	v_add_u32_e32 v3, 0x6d, v3
	v_cmp_lt_i32_e64 s[4:5], s58, v118
	v_cndmask_b32_e64 v131, v214, v131, s[8:9]
	v_cmp_gt_u32_e64 s[8:9], s53, v3
	s_and_b64 s[8:9], s[4:5], s[8:9]
	s_nop 0
	v_cndmask_b32_e64 v3, v214, v135, s[8:9]
	v_cmp_gt_u32_e64 s[8:9], s53, v134
	s_and_b64 vcc, vcc, s[8:9]
	v_cndmask_b32_e32 v123, v214, v123, vcc
	s_and_b64 vcc, s[4:5], s[6:7]
	v_cndmask_b32_e32 v134, v214, v127, vcc
	v_max_f32_e32 v126, v3, v3
	v_max_f32_e32 v127, v131, v131
	v_max_f32_e32 v126, v127, v126
	v_max3_f32 v2, v2, v121, v126
	v_max_f32_e32 v121, v134, v134
	v_max_f32_e32 v126, v123, v123
	v_max_f32_e32 v121, v126, v121
	v_max3_f32 v110, v110, v125, v121
	s_add_i32 s4, s17, 0x2200
	v_mov_b32_e32 v121, v110
	v_mov_b32_e32 v135, v2
	s_waitcnt lgkmcnt(0)
; __device__ __forceinline__ bf16x8 pack8(f32x4 a, f32x4 b) { u32x4 w; w.x = pk2(a[0], a[1]); w.y = pk2(a[2], a[3]); w.z = pk2(b[0], b[1]); w.w = pk2(b[2], b[3]); return __builtin_bit_cast(bf16x8, w); }
; __device__ __forceinline__ void attn_pair_update(QTile& t0, const int mq0, QTile& t1, const int mq1, int mk0, unsigned VSa, LAS unsigned char* KS, int lane) {
;     ...
;     { const float a = __shfl_xor(mx0, 16), b = __shfl_xor(mx1, 16); mx0 = fmaxf(mx0, a); mx1 = fmaxf(mx1, b); }
;     { const float a = __shfl_xor(mx0, 32), b = __shfl_xor(mx1, 32); mx0 = fmaxf(mx0, a); mx1 = fmaxf(mx1, b); }
;     const float mn0 = fmaxf(t0.m, mx0), mn1 = fmaxf(t1.m, mx1);
;     const float mu0 = (mn0 == NEG) ? 0.f : mn0, mu1 = (mn1 == NEG) ? 0.f : mn1;
;     const float al0 = __expf(t0.m - mu0), al1 = __expf(t1.m - mu1);
;     f32x4 p00, p01, p10, p11; float ps0 = 0.f, ps1 = 0.f;
; #pragma unroll
;     for (int j = 0; j < 4; ++j) {
;         p00[j] = __expf(s00[j] - mu0); p01[j] = __expf(s01[j] - mu0); p10[j] = __expf(s10[j] - mu1); p11[j] = __expf(s11[j] - mu1);
;         ps0 += p00[j] + p01[j]; ps1 += p10[j] + p11[j];
;     }
;     t0.l = t0.l * al0 + ps0; t0.m = mn0; t1.l = t1.l * al1 + ps1; t1.m = mn1;
; #pragma unroll
;     for (int dt = 0; dt < 8; ++dt) { t0.o[dt] *= al0; t1.o[dt] *= al1; }
;     const bf16x8 pf0 = pack8(p00, p01), pf1 = pack8(p10, p11);
	s_nop 0
	v_permlane16_swap_b32_e32 v121, v110
	v_permlane16_swap_b32_e32 v135, v2
	v_max_f32_e32 v121, v110, v121
	v_max_f32_e32 v2, v2, v135
	v_mov_b32_e32 v126, v121
	v_mov_b32_e32 v125, v2
	v_mov_b32_e32 v127, v1
	s_nop 0
	v_permlane32_swap_b32_e32 v126, v121
	v_permlane32_swap_b32_e32 v125, v2
	v_max3_f32 v110, v112, v2, v125
	v_cmp_neq_f32_e32 vcc, s55, v110
	v_max3_f32 v2, v0, v121, v126
	v_cndmask_b32_e32 v135, 0, v110, vcc
	v_sub_f32_e32 v112, v112, v135
	v_cmp_neq_f32_e32 vcc, s55, v2
	v_mul_f32_e32 v137, 0x3fb8aa3b, v112
	v_sub_f32_e32 v112, v113, v135
	v_cndmask_b32_e32 v136, 0, v2, vcc
	v_mul_f32_e32 v112, 0x3fb8aa3b, v112
	v_exp_f32_e32 v138, v112
	v_sub_f32_e32 v112, v114, v136
	v_mul_f32_e32 v112, 0x3fb8aa3b, v112
	v_exp_f32_e32 v139, v112
	v_sub_f32_e32 v112, v115, v136
	v_sub_f32_e32 v0, v0, v136
	v_mul_f32_e32 v112, 0x3fb8aa3b, v112
	v_mul_f32_e32 v140, 0x3fb8aa3b, v0
	v_sub_f32_e32 v0, v120, v135
	v_sub_f32_e32 v111, v111, v135
	v_exp_f32_e32 v145, v112
	v_mul_f32_e32 v0, 0x3fb8aa3b, v0
	v_sub_f32_e32 v112, v124, v136
	v_mul_f32_e32 v111, 0x3fb8aa3b, v111
	v_exp_f32_e32 v120, v0
	v_sub_f32_e32 v0, v128, v135
	v_mul_f32_e32 v112, 0x3fb8aa3b, v112
	v_exp_f32_e32 v111, v111
	v_mul_f32_e32 v0, 0x3fb8aa3b, v0
	v_exp_f32_e32 v124, v112
	v_sub_f32_e32 v112, v129, v136
	v_exp_f32_e32 v0, v0
	v_mul_f32_e32 v112, 0x3fb8aa3b, v112
	v_exp_f32_e32 v126, v112
	v_add_f32_e32 v121, v111, v138
	v_add_f32_e32 v125, v139, v145
	v_pk_add_f32 v[112:113], v[120:121], v[0:1]
	v_sub_f32_e32 v3, v3, v135
	v_pk_add_f32 v[114:115], v[112:113], v[112:113] op_sel_hi:[0,1]
	v_pk_add_f32 v[112:113], v[124:125], v[126:127]
	v_mul_f32_e32 v3, 0x3fb8aa3b, v3
	v_pk_add_f32 v[112:113], v[112:113], v[112:113] op_sel_hi:[0,1]
	v_sub_f32_e32 v112, v130, v135
	v_mul_f32_e32 v112, 0x3fb8aa3b, v112
	v_exp_f32_e32 v147, v112
	v_sub_f32_e32 v112, v132, v135
	v_mul_f32_e32 v112, 0x3fb8aa3b, v112
	v_exp_f32_e32 v149, v112
	v_sub_f32_e32 v112, v122, v136
	v_mul_f32_e32 v112, 0x3fb8aa3b, v112
	v_exp_f32_e32 v151, v112
	v_sub_f32_e32 v112, v133, v136
	v_exp_f32_e32 v114, v3
	v_sub_f32_e32 v3, v123, v136
	v_mul_f32_e32 v112, 0x3fb8aa3b, v112
	v_mul_f32_e32 v3, 0x3fb8aa3b, v3
	v_exp_f32_e32 v152, v112
	v_sub_f32_e32 v112, v131, v135
	v_exp_f32_e32 v146, v3
	v_sub_f32_e32 v3, v134, v136
	v_mul_f32_e32 v112, 0x3fb8aa3b, v112
	v_mul_f32_e32 v3, 0x3fb8aa3b, v3
	v_exp_f32_e32 v144, v112
	v_exp_f32_e32 v148, v137
	v_exp_f32_e32 v150, v140
	v_exp_f32_e32 v112, v3
	v_cvt_pk_bf16_f32 v120, v111, v120
	v_pk_mul_f32 v[106:107], v[106:107], v[148:149] op_sel_hi:[1,0]
	v_pk_mul_f32 v[104:105], v[104:105], v[148:149] op_sel_hi:[1,0]
	v_pk_mul_f32 v[102:103], v[102:103], v[150:151] op_sel_hi:[1,0]
	v_pk_mul_f32 v[100:101], v[100:101], v[150:151] op_sel_hi:[1,0]
	v_cvt_pk_bf16_f32 v121, v147, v144
	v_cvt_pk_bf16_f32 v122, v138, v0
	v_cvt_pk_bf16_f32 v123, v149, v114
	v_cvt_pk_bf16_f32 v124, v139, v124
	v_add_u32_e32 v0, s4, v200
	ds_read_b64_tr_b16 v[140:141], v0 offset:0+0
	ds_read_b64_tr_b16 v[142:143], v0 offset:0+4352
	ds_read_b64_tr_b16 v[136:137], v0 offset:0+32
	ds_read_b64_tr_b16 v[138:139], v0 offset:0+4384
	ds_read_b64_tr_b16 v[132:133], v0 offset:0+64
	ds_read_b64_tr_b16 v[134:135], v0 offset:0+4416
	ds_read_b64_tr_b16 v[128:129], v0 offset:0+96
	ds_read_b64_tr_b16 v[130:131], v0 offset:0+4448
	s_waitcnt lgkmcnt(0)
; __device__ __forceinline__ bf16x8 pack8(f32x4 a, f32x4 b) { u32x4 w; w.x = pk2(a[0], a[1]); w.y = pk2(a[2], a[3]); w.z = pk2(b[0], b[1]); w.w = pk2(b[2], b[3]); return __builtin_bit_cast(bf16x8, w); }
; __device__ __forceinline__ void attn_pair_update(QTile& t0, const int mq0, QTile& t1, const int mq1, int mk0, unsigned VSa, LAS unsigned char* KS, int lane) {
;     ...
;     t0.l = t0.l * al0 + ps0; t0.m = mn0; t1.l = t1.l * al1 + ps1; t1.m = mn1;
; #pragma unroll
;     for (int dt = 0; dt < 8; ++dt) { t0.o[dt] *= al0; t1.o[dt] *= al1; }
;     const bf16x8 pf0 = pack8(p00, p01), pf1 = pack8(p10, p11);
;     const unsigned vb = VSa + (unsigned)(((4 * fq + (fr >> 2)) * HP + 4 * (fr & 3)) * 2);
;     s16x4 ra[8];
;     TR8(ra, vb, 0);
; #pragma unroll
;     for (int dt = 0; dt < 4; ++dt) { const bf16x8 vf = cat8(ra[2 * dt], ra[2 * dt + 1]);
;         t0.o[dt] = __builtin_amdgcn_mfma_f32_16x16x32_bf16(vf, pf0, t0.o[dt], 0, 0, 0); t1.o[dt] = __builtin_amdgcn_mfma_f32_16x16x32_bf16(vf, pf1, t1.o[dt], 0, 0, 0); }
;     s16x4 rb[8];
;     TR8(rb, vb, 128);
; #pragma unroll
;     for (int dt = 0; dt < 4; ++dt) { const bf16x8 vf = cat8(rb[2 * dt], rb[2 * dt + 1]);
;         t0.o[4 + dt] = __builtin_amdgcn_mfma_f32_16x16x32_bf16(vf, pf0, t0.o[4 + dt], 0, 0, 0); t1.o[4 + dt] = __builtin_amdgcn_mfma_f32_16x16x32_bf16(vf, pf1, t1.o[4 + dt], 0, 0, 0); }
	v_cvt_pk_bf16_f32 v125, v151, v146
	v_cvt_pk_bf16_f32 v126, v145, v126
	v_cvt_pk_bf16_f32 v127, v152, v112
	v_pk_mul_f32 v[98:99], v[98:99], v[148:149] op_sel_hi:[1,0]
	v_pk_mul_f32 v[96:97], v[96:97], v[148:149] op_sel_hi:[1,0]
	v_pk_mul_f32 v[62:63], v[62:63], v[150:151] op_sel_hi:[1,0]
	v_pk_mul_f32 v[60:61], v[60:61], v[150:151] op_sel_hi:[1,0]
	v_pk_mul_f32 v[90:91], v[90:91], v[148:149] op_sel_hi:[1,0]
	v_pk_mul_f32 v[88:89], v[88:89], v[148:149] op_sel_hi:[1,0]
	v_add_f32_e32 v145, v147, v149
	v_pk_mul_f32 v[50:51], v[50:51], v[150:151] op_sel_hi:[1,0]
	v_pk_mul_f32 v[48:49], v[48:49], v[150:151] op_sel_hi:[1,0]
	v_pk_mul_f32 v[86:87], v[86:87], v[148:149] op_sel_hi:[1,0]
	v_pk_mul_f32 v[84:85], v[84:85], v[148:149] op_sel_hi:[1,0]
	v_pk_mul_f32 v[42:43], v[42:43], v[150:151] op_sel_hi:[1,0]
	v_pk_mul_f32 v[40:41], v[40:41], v[150:151] op_sel_hi:[1,0]
	v_pk_mul_f32 v[78:79], v[78:79], v[148:149] op_sel_hi:[1,0]
	v_pk_mul_f32 v[76:77], v[76:77], v[148:149] op_sel_hi:[1,0]
	v_add_f32_e32 v147, v151, v152
	v_pk_mul_f32 v[34:35], v[34:35], v[150:151] op_sel_hi:[1,0]
	v_pk_mul_f32 v[32:33], v[32:33], v[150:151] op_sel_hi:[1,0]
	v_pk_mul_f32 v[74:75], v[74:75], v[148:149] op_sel_hi:[1,0]
	v_pk_mul_f32 v[72:73], v[72:73], v[148:149] op_sel_hi:[1,0]
	v_pk_mul_f32 v[30:31], v[30:31], v[150:151] op_sel_hi:[1,0]
	v_pk_mul_f32 v[28:29], v[28:29], v[150:151] op_sel_hi:[1,0]
	v_pk_mul_f32 v[70:71], v[70:71], v[148:149] op_sel_hi:[1,0]
	v_pk_mul_f32 v[68:69], v[68:69], v[148:149] op_sel_hi:[1,0]
	v_pk_mul_f32 v[14:15], v[14:15], v[150:151] op_sel_hi:[1,0]
	v_pk_mul_f32 v[12:13], v[12:13], v[150:151] op_sel_hi:[1,0]
	v_pk_mul_f32 v[66:67], v[66:67], v[148:149] op_sel_hi:[1,0]
	v_pk_mul_f32 v[64:65], v[64:65], v[148:149] op_sel_hi:[1,0]
	v_pk_mul_f32 v[6:7], v[6:7], v[150:151] op_sel_hi:[1,0]
	v_pk_mul_f32 v[4:5], v[4:5], v[150:151] op_sel_hi:[1,0]
	v_mfma_f32_16x16x32_bf16 v[104:107], v[140:143], v[120:123], v[104:107]
	v_add_f32_e64 v114, v144, v114
	v_add_f32_e64 v115, v145, v115
	v_pk_add_f32 v[112:113], v[146:147], v[112:113]
	v_add_f32_e32 v3, v114, v115
	v_mfma_f32_16x16x32_bf16 v[100:103], v[140:143], v[124:127], v[100:103]
	v_add_f32_e32 v111, v112, v113
	v_fmac_f32_e32 v3, v119, v148
	v_fmac_f32_e32 v111, v116, v150
	v_mfma_f32_16x16x32_bf16 v[96:99], v[136:139], v[120:123], v[96:99]
	v_mov_b32_e32 v116, v111
	v_mov_b32_e32 v112, v110
	v_mov_b32_e32 v119, v3
	v_mfma_f32_16x16x32_bf16 v[60:63], v[136:139], v[124:127], v[60:63]
	v_mfma_f32_16x16x32_bf16 v[88:91], v[132:135], v[120:123], v[88:91]
	v_mfma_f32_16x16x32_bf16 v[48:51], v[132:135], v[124:127], v[48:51]
	v_mfma_f32_16x16x32_bf16 v[84:87], v[128:131], v[120:123], v[84:87]
	v_mfma_f32_16x16x32_bf16 v[40:43], v[128:131], v[124:127], v[40:43]
	ds_read_b64_tr_b16 v[140:141], v0 offset:128+0
	ds_read_b64_tr_b16 v[142:143], v0 offset:128+4352
	ds_read_b64_tr_b16 v[136:137], v0 offset:128+32
	ds_read_b64_tr_b16 v[138:139], v0 offset:128+4384
	ds_read_b64_tr_b16 v[132:133], v0 offset:128+64
	ds_read_b64_tr_b16 v[134:135], v0 offset:128+4416
	ds_read_b64_tr_b16 v[128:129], v0 offset:128+96
	ds_read_b64_tr_b16 v[130:131], v0 offset:128+4448
	s_waitcnt lgkmcnt(0)
	v_mov_b32_e32 v0, v2
	v_mfma_f32_16x16x32_bf16 v[76:79], v[140:143], v[120:123], v[76:79]
	v_mfma_f32_16x16x32_bf16 v[32:35], v[140:143], v[124:127], v[32:35]
	v_mfma_f32_16x16x32_bf16 v[72:75], v[136:139], v[120:123], v[72:75]
	v_mfma_f32_16x16x32_bf16 v[28:31], v[136:139], v[124:127], v[28:31]
	v_mfma_f32_16x16x32_bf16 v[68:71], v[132:135], v[120:123], v[68:71]
	v_mfma_f32_16x16x32_bf16 v[12:15], v[132:135], v[124:127], v[12:15]
	v_mfma_f32_16x16x32_bf16 v[64:67], v[128:131], v[120:123], v[64:67]
	v_mfma_f32_16x16x32_bf16 v[4:7], v[128:131], v[124:127], v[4:7]

; #define LAS __attribute__((address_space(3)))
; __device__ __forceinline__ void attn_pair_update(QTile& t0, const int mq0, QTile& t1, const int mq1, int mk0, unsigned VSa, LAS unsigned char* KS, int lane) {
;     ...
;         const bf16x8 a0 = *(const LAS bf16x8*)(KS + ((fr)*HP + 32 * kk + 8 * fq) * 2);
;         const bf16x8 a1 = *(const LAS bf16x8*)(KS + ((16 + fr) * HP + 32 * kk + 8 * fq) * 2);
;         s00 = __builtin_amdgcn_mfma_f32_16x16x32_bf16(a0, t0.q[kk], s00, 0, 0, 0);
;         s01 = __builtin_amdgcn_mfma_f32_16x16x32_bf16(a1, t0.q[kk], s01, 0, 0, 0);
;         s10 = __builtin_amdgcn_mfma_f32_16x16x32_bf16(a0, t1.q[kk], s10, 0, 0, 0);
;         s11 = __builtin_amdgcn_mfma_f32_16x16x32_bf16(a1, t1.q[kk], s11, 0, 0, 0);
;     }
;     const float NEG = -__builtin_inff();
;     float mx0 = NEG, mx1 = NEG;
; #pragma unroll
;     for (int j = 0; j < 4; ++j) {
;         const int mk = mk0 + 4 * fq + j, jd0 = mq0 - mk, jd1 = mq1 - mk;
;         const bool kv0 = (mk >= 0), kv1 = (mk + 16 >= 0);
;         if (!((jd0 >= 0) && (jd0 <= 128) && kv0)) s00[j] = NEG;
;         if (!((jd0 - 16 >= 0) && (jd0 - 16 <= 128) && kv1)) s01[j] = NEG;
;         if (!((jd1 >= 0) && (jd1 <= 128) && kv0)) s10[j] = NEG;
;         if (!((jd1 - 16 >= 0) && (jd1 - 16 <= 128) && kv1)) s11[j] = NEG;
;         mx0 = fmaxf(mx0, fmaxf(s00[j], s01[j])); mx1 = fmaxf(mx1, fmaxf(s10[j], s11[j]));
;     }
;     { const float a = __shfl_xor(mx0, 16), b = __shfl_xor(mx1, 16); mx0 = fmaxf(mx0, a); mx1 = fmaxf(mx1, b); }
;     { const float a = __shfl_xor(mx0, 32), b = __shfl_xor(mx1, 32); mx0 = fmaxf(mx0, a); mx1 = fmaxf(mx1, b); }
.LBB0_795:
	ds_read_b128 v[186:189], v223
	ds_read_b128 v[190:193], v223 offset:4352
	ds_read_b128 v[244:247], v223 offset:64
	ds_read_b128 v[248:251], v223 offset:4416
	v_add_u32_e32 v230, 32, v230
	v_add_u32_e32 v183, s12, v228
	s_waitcnt lgkmcnt(3)
	v_mfma_f32_16x16x32_bf16 v[236:239], v[186:189], v[82:85], 0
	v_add_u32_e32 v181, s14, v230
	v_add_u32_e32 v0, 0x80, v183
	v_cmp_lt_i32_e32 vcc, -1, v181
	s_waitcnt lgkmcnt(2)
	v_mfma_f32_16x16x32_bf16 v[240:243], v[190:193], v[82:85], 0
	v_cmp_gt_u32_e64 s[6:7], s53, v0
	s_and_b64 s[6:7], vcc, s[6:7]
	v_mov_b32_e32 v0, s55
	v_mfma_f32_16x16x32_bf16 v[186:189], v[186:189], v[2:5], 0
	v_add_u32_e32 v185, s12, v229
	v_cmp_lt_i32_e64 s[4:5], s52, v181
	v_add_u32_e32 v194, 0x80, v185
	v_mfma_f32_16x16x32_bf16 v[190:193], v[190:193], v[2:5], 0
	v_add_u32_e32 v232, 0x7f, v185
	s_add_i32 s13, s13, 1
	s_sub_i32 s12, s12, 32
	s_waitcnt lgkmcnt(1)
	v_mfma_f32_16x16x32_bf16 v[236:239], v[244:247], v[86:89], v[236:239]
	v_add_u32_e32 v231, 32, v231
	s_waitcnt lgkmcnt(0)
	v_mfma_f32_16x16x32_bf16 v[240:243], v[248:251], v[86:89], v[240:243]
	v_mfma_f32_16x16x32_bf16 v[186:189], v[244:247], v[6:9], v[186:189]
	v_mfma_f32_16x16x32_bf16 v[190:193], v[248:251], v[6:9], v[190:193]
	ds_read_b128 v[244:247], v223 offset:128
	ds_read_b128 v[248:251], v223 offset:4480
	s_waitcnt lgkmcnt(1)
	v_mfma_f32_16x16x32_bf16 v[236:239], v[244:247], v[90:93], v[236:239]
	s_waitcnt lgkmcnt(0)
	v_mfma_f32_16x16x32_bf16 v[240:243], v[248:251], v[90:93], v[240:243]
	v_mfma_f32_16x16x32_bf16 v[186:189], v[244:247], v[10:13], v[186:189]
	v_mfma_f32_16x16x32_bf16 v[190:193], v[248:251], v[10:13], v[190:193]
	ds_read_b128 v[244:247], v223 offset:192
	ds_read_b128 v[248:251], v223 offset:4544
	s_waitcnt lgkmcnt(1)
	v_mfma_f32_16x16x32_bf16 v[236:239], v[244:247], v[94:97], v[236:239]
	s_waitcnt lgkmcnt(0)
	v_mfma_f32_16x16x32_bf16 v[240:243], v[248:251], v[94:97], v[240:243]
	s_nop 5
	v_cndmask_b32_e64 v195, v0, v236, s[6:7]
	v_add_u32_e32 v0, 0x70, v183
	v_cmp_gt_u32_e64 s[6:7], s53, v0
	v_mfma_f32_16x16x32_bf16 v[186:189], v[244:247], v[14:17], v[186:189]
	s_and_b64 s[6:7], s[4:5], s[6:7]
	v_mov_b32_e32 v0, s55
	v_cndmask_b32_e64 v235, v0, v240, s[6:7]
	v_cmp_gt_u32_e64 s[6:7], s53, v194
	v_mfma_f32_16x16x32_bf16 v[190:193], v[248:251], v[14:17], v[190:193]
	s_and_b64 vcc, vcc, s[6:7]
	s_nop 1
	v_cndmask_b32_e32 v186, v0, v186, vcc
	v_add_u32_e32 v0, 0x70, v185
	v_cmp_gt_u32_e32 vcc, s53, v0
	s_and_b64 vcc, s[4:5], vcc
	v_mov_b32_e32 v0, s55
	v_cndmask_b32_e32 v0, v0, v190, vcc
	v_max_f32_e32 v190, v235, v235
	v_max_f32_e32 v194, v195, v195
	v_max_f32_e32 v190, v194, v190
	v_max_f32_e32 v194, v0, v0
	v_max_f32_e32 v227, v186, v186
	v_max_f32_e32 v194, v227, v194
	v_add_u32_e32 v227, 0x7f, v183
	v_cmp_lt_i32_e32 vcc, -2, v181
	v_cmp_gt_u32_e64 s[6:7], s53, v227
	s_and_b64 s[6:7], vcc, s[6:7]
	v_add_u32_e32 v227, 0x6f, v183
	v_cmp_lt_i32_e64 s[4:5], s56, v181
	v_cndmask_b32_e64 v236, v214, v237, s[6:7]
	v_cmp_gt_u32_e64 s[6:7], s53, v227
	s_and_b64 s[6:7], s[4:5], s[6:7]
	v_add_u32_e32 v227, 0x6f, v185
	v_cndmask_b32_e64 v237, v214, v241, s[6:7]
	v_cmp_gt_u32_e64 s[6:7], s53, v232
	s_and_b64 vcc, vcc, s[6:7]
	v_cndmask_b32_e32 v187, v214, v187, vcc
	v_cmp_gt_u32_e32 vcc, s53, v227
	s_and_b64 vcc, s[4:5], vcc
	v_max_f32_e32 v227, v237, v237
	v_max_f32_e32 v232, v236, v236
	v_cndmask_b32_e32 v191, v214, v191, vcc
	v_max_f32_e32 v227, v232, v227
	v_max3_f32 v190, v190, s55, v227
	v_max_f32_e32 v227, v191, v191
	v_max_f32_e32 v232, v187, v187
	v_max_f32_e32 v227, v232, v227
	v_max3_f32 v194, v194, s55, v227
	v_add_u32_e32 v227, 0x7e, v183
	v_cmp_lt_i32_e32 vcc, -3, v181
	v_cmp_gt_u32_e64 s[6:7], s53, v227
	s_and_b64 s[6:7], vcc, s[6:7]
	v_add_u32_e32 v227, 0x6e, v183
	v_cmp_lt_i32_e64 s[4:5], s57, v181
	v_cndmask_b32_e64 v238, v214, v238, s[6:7]
	v_cmp_gt_u32_e64 s[6:7], s53, v227
	v_add_u32_e32 v232, 0x7e, v185
	s_and_b64 s[6:7], s[4:5], s[6:7]
	v_cndmask_b32_e64 v240, v214, v242, s[6:7]
	v_cmp_gt_u32_e64 s[6:7], s53, v232
	s_and_b64 vcc, vcc, s[6:7]
	v_cndmask_b32_e32 v241, v214, v188, vcc
	v_add_u32_e32 v188, 0x6e, v185
	v_cmp_gt_u32_e32 vcc, s53, v188
	s_and_b64 vcc, s[4:5], vcc
	v_max_f32_e32 v188, v240, v240
	v_cndmask_b32_e32 v192, v214, v192, vcc
	v_max_f32_e32 v227, v238, v238
	v_max_f32_e32 v188, v227, v188
	v_max_f32_e32 v227, v192, v192
	v_max_f32_e32 v232, v241, v241
	v_max_f32_e32 v227, v232, v227
	v_add_u32_e32 v232, 0x7d, v183
	v_cmp_lt_i32_e32 vcc, -4, v181
	v_cmp_gt_u32_e64 s[6:7], s53, v232
	s_and_b64 s[6:7], vcc, s[6:7]
	v_add_u32_e32 v183, 0x6d, v183
	v_cmp_lt_i32_e64 s[4:5], s58, v181
	v_cndmask_b32_e64 v181, v214, v239, s[6:7]
	v_cmp_gt_u32_e64 s[6:7], s53, v183
	v_add_u32_e32 v242, 0x7d, v185
	s_and_b64 s[6:7], s[4:5], s[6:7]
	v_cndmask_b32_e64 v239, v214, v243, s[6:7]
	v_cmp_gt_u32_e64 s[6:7], s53, v242
	s_and_b64 vcc, vcc, s[6:7]
	v_add_u32_e32 v183, 0x6d, v185
	v_cndmask_b32_e32 v242, v214, v189, vcc
	v_cmp_gt_u32_e32 vcc, s53, v183
	s_and_b64 vcc, s[4:5], vcc
	v_max_f32_e32 v183, v239, v239
	v_max_f32_e32 v185, v181, v181
	v_cndmask_b32_e32 v243, v214, v193, vcc
	v_max_f32_e32 v183, v185, v183
	v_max3_f32 v183, v190, v188, v183
	v_max_f32_e32 v185, v243, v243
	v_max_f32_e32 v188, v242, v242
	v_max_f32_e32 v185, v188, v185
	v_max3_f32 v185, v194, v227, v185
	v_mov_b32_e32 v188, v183
	v_mov_b32_e32 v189, v185
	s_cmp_lt_u32 s13, 5
	s_waitcnt lgkmcnt(0)
; __device__ __forceinline__ bf16x8 pack8(f32x4 a, f32x4 b) { u32x4 w; w.x = pk2(a[0], a[1]); w.y = pk2(a[2], a[3]); w.z = pk2(b[0], b[1]); w.w = pk2(b[2], b[3]); return __builtin_bit_cast(bf16x8, w); }
; __device__ __forceinline__ void attn_pair_update(QTile& t0, const int mq0, QTile& t1, const int mq1, int mk0, unsigned VSa, LAS unsigned char* KS, int lane) {
;     ...
;     { const float a = __shfl_xor(mx0, 16), b = __shfl_xor(mx1, 16); mx0 = fmaxf(mx0, a); mx1 = fmaxf(mx1, b); }
;     { const float a = __shfl_xor(mx0, 32), b = __shfl_xor(mx1, 32); mx0 = fmaxf(mx0, a); mx1 = fmaxf(mx1, b); }
;     const float mn0 = fmaxf(t0.m, mx0), mn1 = fmaxf(t1.m, mx1);
;     const float mu0 = (mn0 == NEG) ? 0.f : mn0, mu1 = (mn1 == NEG) ? 0.f : mn1;
;     const float al0 = __expf(t0.m - mu0), al1 = __expf(t1.m - mu1);
;     f32x4 p00, p01, p10, p11; float ps0 = 0.f, ps1 = 0.f;
; #pragma unroll
;     for (int j = 0; j < 4; ++j) {
;         p00[j] = __expf(s00[j] - mu0); p01[j] = __expf(s01[j] - mu0); p10[j] = __expf(s10[j] - mu1); p11[j] = __expf(s11[j] - mu1);
;         ps0 += p00[j] + p01[j]; ps1 += p10[j] + p11[j];
;     }
;     t0.l = t0.l * al0 + ps0; t0.m = mn0; t1.l = t1.l * al1 + ps1; t1.m = mn1;
; #pragma unroll
;     for (int dt = 0; dt < 8; ++dt) { t0.o[dt] *= al0; t1.o[dt] *= al1; }
;     const bf16x8 pf0 = pack8(p00, p01), pf1 = pack8(p10, p11);
;     const unsigned vb = VSa + (unsigned)(((4 * fq + (fr >> 2)) * HP + 4 * (fr & 3)) * 2);
;     s16x4 ra[8];
;     TR8(ra, vb, 0);
; #pragma unroll
;     for (int dt = 0; dt < 4; ++dt) { const bf16x8 vf = cat8(ra[2 * dt], ra[2 * dt + 1]);
;         t0.o[dt] = __builtin_amdgcn_mfma_f32_16x16x32_bf16(vf, pf0, t0.o[dt], 0, 0, 0); t1.o[dt] = __builtin_amdgcn_mfma_f32_16x16x32_bf16(vf, pf1, t1.o[dt], 0, 0, 0); }
	s_nop 0
	v_permlane16_swap_b32_e32 v188, v183
	v_permlane16_swap_b32_e32 v189, v185
	v_max_f32_e32 v183, v183, v188
	v_max_f32_e32 v185, v185, v189
	v_mov_b32_e32 v188, v183
	v_mov_b32_e32 v189, v185
	s_nop 1
	v_permlane32_swap_b32_e32 v188, v183
	v_permlane32_swap_b32_e32 v189, v185
	v_max3_f32 v232, v182, v183, v188
	v_max3_f32 v227, v184, v185, v189
	v_cmp_neq_f32_e32 vcc, s55, v232
	s_nop 1
	v_cndmask_b32_e32 v244, 0, v232, vcc
	v_cmp_neq_f32_e32 vcc, s55, v227
	v_sub_f32_e32 v182, v182, v244
	v_mul_f32_e32 v246, 0x3fb8aa3b, v182
	v_cndmask_b32_e32 v245, 0, v227, vcc
	v_sub_f32_e32 v182, v184, v245
	v_mul_f32_e32 v247, 0x3fb8aa3b, v182
	v_sub_f32_e32 v182, v195, v244
	v_mul_f32_e32 v182, 0x3fb8aa3b, v182
	v_sub_f32_e32 v0, v0, v245
	v_exp_f32_e32 v248, v182
	v_sub_f32_e32 v182, v235, v244
	v_mul_f32_e32 v0, 0x3fb8aa3b, v0
	v_mul_f32_e32 v182, 0x3fb8aa3b, v182
	v_exp_f32_e32 v251, v0
	v_sub_f32_e32 v0, v236, v244
	v_exp_f32_e32 v249, v182
	v_sub_f32_e32 v182, v186, v245
	v_mul_f32_e32 v0, 0x3fb8aa3b, v0
	v_mul_f32_e32 v182, 0x3fb8aa3b, v182
	v_exp_f32_e32 v184, v0
	v_sub_f32_e32 v0, v237, v244
	v_exp_f32_e32 v250, v182
	v_mul_f32_e32 v0, 0x3fb8aa3b, v0
	v_sub_f32_e32 v182, v187, v245
	v_sub_f32_e32 v186, v191, v245
	v_exp_f32_e32 v0, v0
	v_mul_f32_e32 v182, 0x3fb8aa3b, v182
	v_mul_f32_e32 v186, 0x3fb8aa3b, v186
	v_exp_f32_e32 v182, v182
	v_exp_f32_e32 v186, v186
	v_add_f32_e32 v185, v248, v249
	v_add_f32_e32 v183, v250, v251
	v_pk_add_f32 v[188:189], v[184:185], v[0:1]
	v_mov_b32_e32 v187, v1
	v_pk_add_f32 v[190:191], v[188:189], v[188:189] op_sel_hi:[0,1]
	v_pk_add_f32 v[188:189], v[182:183], v[186:187]
	v_sub_f32_e32 v183, v238, v244
	v_mul_f32_e32 v183, 0x3fb8aa3b, v183
	v_sub_f32_e32 v181, v181, v244
	v_exp_f32_e32 v187, v183
	v_sub_f32_e32 v183, v240, v244
	v_mul_f32_e32 v181, 0x3fb8aa3b, v181
	v_mul_f32_e32 v183, 0x3fb8aa3b, v183
	v_exp_f32_e32 v194, v181
	v_sub_f32_e32 v181, v239, v244
	v_exp_f32_e32 v240, v183
	v_sub_f32_e32 v183, v241, v245
	v_mul_f32_e32 v181, 0x3fb8aa3b, v181
	v_mul_f32_e32 v183, 0x3fb8aa3b, v183
	v_exp_f32_e32 v190, v181
	v_sub_f32_e32 v181, v242, v245
	v_exp_f32_e32 v241, v183
	v_sub_f32_e32 v183, v192, v245
	v_mul_f32_e32 v181, 0x3fb8aa3b, v181
	v_mul_f32_e32 v183, 0x3fb8aa3b, v183
	v_exp_f32_e32 v192, v181
	v_sub_f32_e32 v181, v243, v245
	v_pk_add_f32 v[188:189], v[188:189], v[188:189] op_sel_hi:[0,1]
	v_exp_f32_e32 v252, v183
	v_mul_f32_e32 v181, 0x3fb8aa3b, v181
	v_exp_f32_e32 v188, v181
	v_add_f32_e32 v195, v187, v240
	v_add_f32_e32 v193, v241, v252
	v_pk_add_f32 v[236:237], v[194:195], v[190:191]
	v_exp_f32_e32 v238, v247
	v_add_f32_e32 v185, v236, v237
	v_pk_add_f32 v[236:237], v[192:193], v[188:189]
	v_cvt_pk_bf16_f32 v235, v187, v194
	v_add_f32_e32 v183, v236, v237
	v_exp_f32_e32 v236, v246
	v_fmac_f32_e32 v183, v233, v238
	v_pk_mul_f32 v[36:37], v[36:37], v[238:239] op_sel_hi:[1,0]
	v_pk_mul_f32 v[34:35], v[34:35], v[238:239] op_sel_hi:[1,0]
	v_fmac_f32_e32 v185, v234, v236
	v_pk_mul_f32 v[76:77], v[76:77], v[236:237] op_sel_hi:[1,0]
	v_pk_mul_f32 v[74:75], v[74:75], v[236:237] op_sel_hi:[1,0]
	v_pk_mul_f32 v[44:45], v[44:45], v[236:237] op_sel_hi:[1,0]
	v_pk_mul_f32 v[42:43], v[42:43], v[236:237] op_sel_hi:[1,0]
	v_pk_mul_f32 v[20:21], v[20:21], v[238:239] op_sel_hi:[1,0]
	v_pk_mul_f32 v[18:19], v[18:19], v[238:239] op_sel_hi:[1,0]
	v_pk_mul_f32 v[52:53], v[52:53], v[236:237] op_sel_hi:[1,0]
	v_pk_mul_f32 v[50:51], v[50:51], v[236:237] op_sel_hi:[1,0]
	v_pk_mul_f32 v[24:25], v[24:25], v[238:239] op_sel_hi:[1,0]
	v_pk_mul_f32 v[22:23], v[22:23], v[238:239] op_sel_hi:[1,0]
	v_pk_mul_f32 v[60:61], v[60:61], v[236:237] op_sel_hi:[1,0]
	v_pk_mul_f32 v[58:59], v[58:59], v[236:237] op_sel_hi:[1,0]
	v_pk_mul_f32 v[28:29], v[28:29], v[238:239] op_sel_hi:[1,0]
	v_pk_mul_f32 v[26:27], v[26:27], v[238:239] op_sel_hi:[1,0]
	v_pk_mul_f32 v[64:65], v[64:65], v[236:237] op_sel_hi:[1,0]
	v_pk_mul_f32 v[62:63], v[62:63], v[236:237] op_sel_hi:[1,0]
	v_pk_mul_f32 v[32:33], v[32:33], v[238:239] op_sel_hi:[1,0]
	v_pk_mul_f32 v[30:31], v[30:31], v[238:239] op_sel_hi:[1,0]
	v_pk_mul_f32 v[68:69], v[68:69], v[236:237] op_sel_hi:[1,0]
	v_pk_mul_f32 v[66:67], v[66:67], v[236:237] op_sel_hi:[1,0]
	v_pk_mul_f32 v[40:41], v[40:41], v[238:239] op_sel_hi:[1,0]
	v_pk_mul_f32 v[38:39], v[38:39], v[238:239] op_sel_hi:[1,0]
	v_pk_mul_f32 v[72:73], v[72:73], v[236:237] op_sel_hi:[1,0]
	v_pk_mul_f32 v[70:71], v[70:71], v[236:237] op_sel_hi:[1,0]
	v_pk_mul_f32 v[48:49], v[48:49], v[238:239] op_sel_hi:[1,0]
	v_pk_mul_f32 v[46:47], v[46:47], v[238:239] op_sel_hi:[1,0]
	v_pk_mul_f32 v[80:81], v[80:81], v[236:237] op_sel_hi:[1,0]
	v_pk_mul_f32 v[78:79], v[78:79], v[236:237] op_sel_hi:[1,0]
	v_pk_mul_f32 v[56:57], v[56:57], v[238:239] op_sel_hi:[1,0]
	v_pk_mul_f32 v[54:55], v[54:55], v[238:239] op_sel_hi:[1,0]
	v_cvt_pk_bf16_f32 v234, v248, v184
	v_cvt_pk_bf16_f32 v236, v249, v0
	v_cvt_pk_bf16_f32 v237, v240, v190
	v_cvt_pk_bf16_f32 v190, v250, v182
	v_cvt_pk_bf16_f32 v191, v241, v192
	v_cvt_pk_bf16_f32 v192, v251, v186
	v_cvt_pk_bf16_f32 v193, v252, v188
	ds_read_b64_tr_b16 v[246:247], v206 offset:0+0
	ds_read_b64_tr_b16 v[248:249], v206 offset:0+4352
	ds_read_b64_tr_b16 v[242:243], v206 offset:0+32
	ds_read_b64_tr_b16 v[244:245], v206 offset:0+4384
	ds_read_b64_tr_b16 v[238:239], v206 offset:0+64
	ds_read_b64_tr_b16 v[240:241], v206 offset:0+4416
	ds_read_b64_tr_b16 v[186:187], v206 offset:0+96
	ds_read_b64_tr_b16 v[188:189], v206 offset:0+4448
	s_waitcnt lgkmcnt(0)
; __device__ __forceinline__ void attn_pair_update(QTile& t0, const int mq0, QTile& t1, const int mq1, int mk0, unsigned VSa, LAS unsigned char* KS, int lane) {
;     ...
;     s16x4 rb[8];
;     TR8(rb, vb, 128);
; #pragma unroll
;     for (int dt = 0; dt < 4; ++dt) { const bf16x8 vf = cat8(rb[2 * dt], rb[2 * dt + 1]);
;         t0.o[4 + dt] = __builtin_amdgcn_mfma_f32_16x16x32_bf16(vf, pf0, t0.o[4 + dt], 0, 0, 0); t1.o[4 + dt] = __builtin_amdgcn_mfma_f32_16x16x32_bf16(vf, pf1, t1.o[4 + dt], 0, 0, 0); }
	s_nop 0
	v_mfma_f32_16x16x32_bf16 v[74:77], v[246:249], v[234:237], v[74:77]
	v_mfma_f32_16x16x32_bf16 v[34:37], v[246:249], v[190:193], v[34:37]
	v_mfma_f32_16x16x32_bf16 v[42:45], v[242:245], v[234:237], v[42:45]
	v_mfma_f32_16x16x32_bf16 v[18:21], v[242:245], v[190:193], v[18:21]
	v_mfma_f32_16x16x32_bf16 v[50:53], v[238:241], v[234:237], v[50:53]
	v_mfma_f32_16x16x32_bf16 v[22:25], v[238:241], v[190:193], v[22:25]
	v_mfma_f32_16x16x32_bf16 v[58:61], v[186:189], v[234:237], v[58:61]
	v_mfma_f32_16x16x32_bf16 v[26:29], v[186:189], v[190:193], v[26:29]
	ds_read_b64_tr_b16 v[246:247], v206 offset:128+0
	ds_read_b64_tr_b16 v[248:249], v206 offset:128+4352
	ds_read_b64_tr_b16 v[242:243], v206 offset:128+32
	ds_read_b64_tr_b16 v[244:245], v206 offset:128+4384
	ds_read_b64_tr_b16 v[238:239], v206 offset:128+64
	ds_read_b64_tr_b16 v[240:241], v206 offset:128+4416
	ds_read_b64_tr_b16 v[186:187], v206 offset:128+96
	ds_read_b64_tr_b16 v[188:189], v206 offset:128+4448
	s_waitcnt lgkmcnt(0)
	s_waitcnt lgkmcnt(0)
	s_nop 0
	v_mfma_f32_16x16x32_bf16 v[62:65], v[246:249], v[234:237], v[62:65]
	v_mfma_f32_16x16x32_bf16 v[30:33], v[246:249], v[190:193], v[30:33]
	v_mfma_f32_16x16x32_bf16 v[66:69], v[242:245], v[234:237], v[66:69]
	v_mfma_f32_16x16x32_bf16 v[38:41], v[242:245], v[190:193], v[38:41]
	v_mfma_f32_16x16x32_bf16 v[70:73], v[238:241], v[234:237], v[70:73]
	v_mfma_f32_16x16x32_bf16 v[46:49], v[238:241], v[190:193], v[46:49]
	v_mfma_f32_16x16x32_bf16 v[78:81], v[186:189], v[234:237], v[78:81]
	v_mfma_f32_16x16x32_bf16 v[54:57], v[186:189], v[190:193], v[54:57]
	s_cbranch_scc0 .LBB0_797
	v_mov_b32_e32 v184, v227
	v_mov_b32_e32 v233, v183
	v_mov_b32_e32 v182, v232
	v_mov_b32_e32 v234, v185
	s_branch .LBB0_793

; #define LAS __attribute__((address_space(3)))
; __device__ __forceinline__ void attn_tile_update(QTile& t, const int mq, int mk0, unsigned VSa, LAS unsigned char* KS, int lane) {
;     ...
;         const bf16x8 a0 = *(const LAS bf16x8*)(KS + ((fr)*HP + 32 * kk + 8 * fq) * 2);
;         const bf16x8 a1 = *(const LAS bf16x8*)(KS + ((16 + fr) * HP + 32 * kk + 8 * fq) * 2);
;         s0 = __builtin_amdgcn_mfma_f32_16x16x32_bf16(a0, t.q[kk], s0, 0, 0, 0);
;         s1 = __builtin_amdgcn_mfma_f32_16x16x32_bf16(a1, t.q[kk], s1, 0, 0, 0);
;     }
;     const float NEG = -__builtin_inff();
;     float mx = NEG;
;     bool v0[4], v1[4];
; #pragma unroll
;     for (int j = 0; j < 4; ++j) {
;         const int mk = mk0 + 4 * fq + j, jd = mq - mk;
;         v0[j] = (jd >= 0) && (jd <= 128) && (mk >= 0);
;         v1[j] = (jd - 16 >= 0) && (jd - 16 <= 128) && (mk + 16 >= 0);
;         if (v0[j]) mx = fmaxf(mx, s0[j]);
;         if (v1[j]) mx = fmaxf(mx, s1[j]);
;     }
;     mx = fmaxf(mx, __shfl_xor(mx, 16)); mx = fmaxf(mx, __shfl_xor(mx, 32));
.LBB0_802:
	ds_read_b128 v[190:193], v223
	ds_read_b128 v[228:231], v223 offset:64
	ds_read_b128 v[234:237], v223 offset:4352
	ds_read_b128 v[238:241], v223 offset:4416
	v_add_u32_e32 v0, s70, v188
	v_add_u32_e32 v181, 0x90, v0
	s_waitcnt lgkmcnt(3)
	v_mfma_f32_16x16x32_bf16 v[190:193], v[190:193], v[82:85], 0
	v_cmp_lt_i32_e32 vcc, -1, v187
	v_cmp_gt_u32_e64 s[6:7], s53, v181
	v_add_u32_e32 v182, 0x80, v0
	s_waitcnt lgkmcnt(1)
	v_mfma_f32_16x16x32_bf16 v[234:237], v[234:237], v[82:85], 0
	s_and_b64 vcc, vcc, s[6:7]
	v_cmp_lt_i32_e64 s[4:5], s52, v187
	v_cmp_gt_u32_e64 s[8:9], s53, v182
	v_mfma_f32_16x16x32_bf16 v[190:193], v[228:231], v[86:89], v[190:193]
	ds_read_b128 v[228:231], v223 offset:128
	ds_read_b128 v[242:245], v223 offset:192
	s_and_b64 s[4:5], s[8:9], s[4:5]
	v_cmp_lt_i32_e64 s[8:9], -2, v187
	s_waitcnt lgkmcnt(2)
	v_mfma_f32_16x16x32_bf16 v[234:237], v[238:241], v[86:89], v[234:237]
	ds_read_b128 v[238:241], v223 offset:4480
	ds_read_b128 v[246:249], v223 offset:4544
	v_cmp_lt_i32_e64 s[12:13], s56, v187
	v_cmp_lt_i32_e64 s[16:17], s57, v187
	s_waitcnt lgkmcnt(3)
	v_mfma_f32_16x16x32_bf16 v[190:193], v[228:231], v[90:93], v[190:193]
	v_cmp_lt_i32_e64 s[20:21], s58, v187
	s_sub_i32 s70, s70, 32
	s_add_i32 s71, s71, 1
	s_waitcnt lgkmcnt(1)
	v_mfma_f32_16x16x32_bf16 v[228:231], v[238:241], v[90:93], v[234:237]
	v_add_u32_e32 v189, 32, v189
	v_mfma_f32_16x16x32_bf16 v[190:193], v[242:245], v[94:97], v[190:193]
	s_waitcnt lgkmcnt(0)
	v_mfma_f32_16x16x32_bf16 v[228:231], v[246:249], v[94:97], v[228:231]
	s_nop 5
	v_max_f32_e32 v181, v190, v190
	v_max_f32_e32 v181, 0xff800000, v181
	v_cndmask_b32_e32 v181, v214, v181, vcc
	v_max_f32_e32 v182, v228, v228
	v_max_f32_e32 v182, v181, v182
	v_cndmask_b32_e64 v181, v181, v182, s[4:5]
	v_add_u32_e32 v182, 0x8f, v0
	v_cmp_gt_u32_e64 s[6:7], s53, v182
	v_add_u32_e32 v182, 0x7f, v0
	v_cmp_gt_u32_e64 s[10:11], s53, v182
	v_max_f32_e32 v182, v191, v191
	v_max_f32_e32 v182, v181, v182
	s_and_b64 s[6:7], s[8:9], s[6:7]
	v_cndmask_b32_e64 v181, v181, v182, s[6:7]
	v_max_f32_e32 v182, v229, v229
	v_max_f32_e32 v182, v181, v182
	s_and_b64 s[8:9], s[10:11], s[12:13]
	v_cndmask_b32_e64 v181, v181, v182, s[8:9]
	v_add_u32_e32 v182, 0x8e, v0
	v_cmp_gt_u32_e64 s[10:11], s53, v182
	v_add_u32_e32 v182, 0x7e, v0
	v_cmp_lt_i32_e64 s[12:13], -3, v187
	v_cmp_gt_u32_e64 s[14:15], s53, v182
	v_max_f32_e32 v182, v192, v192
	v_max_f32_e32 v182, v181, v182
	s_and_b64 s[10:11], s[12:13], s[10:11]
	v_cndmask_b32_e64 v181, v181, v182, s[10:11]
	v_max_f32_e32 v182, v181, v181
	v_max_f32_e32 v194, v230, v230
	v_max_f32_e32 v182, v182, v194
	s_and_b64 s[12:13], s[14:15], s[16:17]
	v_cndmask_b32_e64 v181, v181, v182, s[12:13]
	v_add_u32_e32 v182, 0x8d, v0
	v_add_u32_e32 v0, 0x7d, v0
	v_cmp_gt_u32_e64 s[14:15], s53, v182
	v_cmp_lt_i32_e64 s[16:17], -4, v187
	v_cmp_gt_u32_e64 s[18:19], s53, v0
	v_max_f32_e32 v0, v181, v181
	v_max_f32_e32 v182, v193, v193
	v_max_f32_e32 v0, v0, v182
	s_and_b64 s[14:15], s[16:17], s[14:15]
	v_cndmask_b32_e64 v0, v181, v0, s[14:15]
	v_max_f32_e32 v181, v0, v0
	v_max_f32_e32 v182, v231, v231
	v_max_f32_e32 v181, v181, v182
	s_and_b64 s[16:17], s[18:19], s[20:21]
	v_cndmask_b32_e64 v0, v0, v181, s[16:17]
	v_max_f32_e32 v0, v0, v0
	v_add_u32_e32 v187, 32, v187
	s_cmp_lt_u32 s71, 4
	v_mov_b32_e32 v181, v0
	s_waitcnt lgkmcnt(0)
; __device__ __forceinline__ bf16x8 pack8(f32x4 a, f32x4 b) { u32x4 w; w.x = pk2(a[0], a[1]); w.y = pk2(a[2], a[3]); w.z = pk2(b[0], b[1]); w.w = pk2(b[2], b[3]); return __builtin_bit_cast(bf16x8, w); }
; __device__ __forceinline__ void attn_tile_update(QTile& t, const int mq, int mk0, unsigned VSa, LAS unsigned char* KS, int lane) {
;     ...
;     mx = fmaxf(mx, __shfl_xor(mx, 16)); mx = fmaxf(mx, __shfl_xor(mx, 32));
;     const float mnew = fmaxf(t.m, mx);
;     const float muse = (mnew == NEG) ? 0.f : mnew;
;     const float alpha = __expf(t.m - muse);
;     f32x4 p0, p1; float ps = 0.f;
; #pragma unroll
;     for (int j = 0; j < 4; ++j) { p0[j] = v0[j] ? __expf(s0[j] - muse) : 0.f; p1[j] = v1[j] ? __expf(s1[j] - muse) : 0.f; ps += p0[j] + p1[j]; }
;     t.l = t.l * alpha + ps; t.m = mnew;
; #pragma unroll
;     for (int dt = 0; dt < 8; ++dt) t.o[dt] *= alpha;
;     const bf16x8 pf = pack8(p0, p1);
;     const unsigned vb = VSa + (unsigned)(((4 * fq + (fr >> 2)) * HP + 4 * (fr & 3)) * 2);
;     s16x4 ra[8], rb[8];
;     TR8(ra, vb, 0);
;     TR8(rb, vb, 128);
; #pragma unroll
;     for (int dt = 0; dt < 4; ++dt) t.o[dt] = __builtin_amdgcn_mfma_f32_16x16x32_bf16(cat8(ra[2 * dt], ra[2 * dt + 1]), pf, t.o[dt], 0, 0, 0);
; #pragma unroll
;     for (int dt = 0; dt < 4; ++dt) t.o[4 + dt] = __builtin_amdgcn_mfma_f32_16x16x32_bf16(cat8(rb[2 * dt], rb[2 * dt + 1]), pf, t.o[4 + dt], 0, 0, 0);
	s_nop 0
	v_permlane16_swap_b32_e32 v181, v0
	v_max_f32_e32 v0, v0, v181
	v_mov_b32_e32 v181, v0
	s_nop 1
	v_permlane32_swap_b32_e32 v181, v0
	v_max3_f32 v0, v232, v0, v181
	v_cmp_neq_f32_e64 s[18:19], s55, v0
	s_nop 1
	v_cndmask_b32_e64 v181, 0, v0, s[18:19]
	v_sub_f32_e32 v182, v190, v181
	v_sub_f32_e32 v190, v228, v181
	v_mul_f32_e32 v190, 0x3fb8aa3b, v190
	v_exp_f32_e32 v190, v190
	v_mul_f32_e32 v182, 0x3fb8aa3b, v182
	v_exp_f32_e32 v182, v182
	v_sub_f32_e32 v194, v232, v181
	v_cndmask_b32_e64 v195, 0, v190, s[4:5]
	v_sub_f32_e32 v190, v191, v181
	v_sub_f32_e32 v191, v229, v181
	v_mul_f32_e32 v191, 0x3fb8aa3b, v191
	v_exp_f32_e32 v191, v191
	v_mul_f32_e32 v190, 0x3fb8aa3b, v190
	v_exp_f32_e32 v190, v190
	v_cndmask_b32_e32 v182, 0, v182, vcc
	v_cndmask_b32_e64 v229, 0, v191, s[8:9]
	v_sub_f32_e32 v191, v192, v181
	v_sub_f32_e32 v192, v230, v181
	v_mul_f32_e32 v192, 0x3fb8aa3b, v192
	v_exp_f32_e32 v192, v192
	v_add_f32_e32 v228, v182, v195
	v_cndmask_b32_e64 v190, 0, v190, s[6:7]
	v_add_f32_e32 v228, 0, v228
	v_add_f32_e32 v230, v190, v229
	v_add_f32_e32 v244, v230, v228
	v_cndmask_b32_e64 v228, 0, v192, s[12:13]
	v_sub_f32_e32 v192, v193, v181
	v_sub_f32_e32 v181, v231, v181
	v_mul_f32_e32 v191, 0x3fb8aa3b, v191
	v_mul_f32_e32 v192, 0x3fb8aa3b, v192
	v_mul_f32_e32 v181, 0x3fb8aa3b, v181
	v_mul_f32_e32 v194, 0x3fb8aa3b, v194
	v_exp_f32_e32 v191, v191
	v_exp_f32_e32 v192, v192
	v_exp_f32_e32 v181, v181
	v_exp_f32_e32 v194, v194
	v_cndmask_b32_e64 v191, 0, v191, s[10:11]
	v_cndmask_b32_e64 v246, 0, v192, s[14:15]
	v_cndmask_b32_e64 v181, 0, v181, s[16:17]
	v_add_f32_e32 v245, v191, v228
	v_pk_mul_f32 v[76:77], v[76:77], v[194:195] op_sel_hi:[1,0]
	v_pk_mul_f32 v[74:75], v[74:75], v[194:195] op_sel_hi:[1,0]
	v_cvt_pk_bf16_f32 v190, v182, v190
	v_cvt_pk_bf16_f32 v191, v191, v246
	v_cvt_pk_bf16_f32 v192, v195, v229
	v_cvt_pk_bf16_f32 v193, v228, v181
	ds_read_b64_tr_b16 v[240:241], v206 offset:0+0
	ds_read_b64_tr_b16 v[242:243], v206 offset:0+4352
	ds_read_b64_tr_b16 v[236:237], v206 offset:0+32
	ds_read_b64_tr_b16 v[238:239], v206 offset:0+4384
	ds_read_b64_tr_b16 v[232:233], v206 offset:0+64
	ds_read_b64_tr_b16 v[234:235], v206 offset:0+4416
	ds_read_b64_tr_b16 v[228:229], v206 offset:0+96
	ds_read_b64_tr_b16 v[230:231], v206 offset:0+4448
	s_waitcnt lgkmcnt(0)
	v_pk_mul_f32 v[44:45], v[44:45], v[194:195] op_sel_hi:[1,0]
	v_pk_mul_f32 v[42:43], v[42:43], v[194:195] op_sel_hi:[1,0]
	v_pk_mul_f32 v[52:53], v[52:53], v[194:195] op_sel_hi:[1,0]
	v_pk_mul_f32 v[50:51], v[50:51], v[194:195] op_sel_hi:[1,0]
	v_pk_mul_f32 v[60:61], v[60:61], v[194:195] op_sel_hi:[1,0]
	v_pk_mul_f32 v[58:59], v[58:59], v[194:195] op_sel_hi:[1,0]
	v_pk_mul_f32 v[64:65], v[64:65], v[194:195] op_sel_hi:[1,0]
	v_pk_mul_f32 v[62:63], v[62:63], v[194:195] op_sel_hi:[1,0]
	v_pk_mul_f32 v[68:69], v[68:69], v[194:195] op_sel_hi:[1,0]
	v_pk_mul_f32 v[66:67], v[66:67], v[194:195] op_sel_hi:[1,0]
	v_pk_mul_f32 v[72:73], v[72:73], v[194:195] op_sel_hi:[1,0]
	v_pk_mul_f32 v[70:71], v[70:71], v[194:195] op_sel_hi:[1,0]
	v_pk_mul_f32 v[80:81], v[80:81], v[194:195] op_sel_hi:[1,0]
	v_pk_mul_f32 v[78:79], v[78:79], v[194:195] op_sel_hi:[1,0]
	v_mfma_f32_16x16x32_bf16 v[74:77], v[240:243], v[190:193], v[74:77]
	v_add_f32_e32 v182, v245, v244
	v_add_f32_e32 v181, v246, v181
	v_add_f32_e32 v182, v181, v182
	v_mfma_f32_16x16x32_bf16 v[42:45], v[236:239], v[190:193], v[42:45]
	v_fmac_f32_e32 v182, v185, v194
	v_mfma_f32_16x16x32_bf16 v[50:53], v[232:235], v[190:193], v[50:53]
	v_mfma_f32_16x16x32_bf16 v[58:61], v[228:231], v[190:193], v[58:61]
	ds_read_b64_tr_b16 v[240:241], v206 offset:128+0
	ds_read_b64_tr_b16 v[242:243], v206 offset:128+4352
	ds_read_b64_tr_b16 v[236:237], v206 offset:128+32
	ds_read_b64_tr_b16 v[238:239], v206 offset:128+4384
	ds_read_b64_tr_b16 v[232:233], v206 offset:128+64
	ds_read_b64_tr_b16 v[234:235], v206 offset:128+4416
	ds_read_b64_tr_b16 v[228:229], v206 offset:128+96
	ds_read_b64_tr_b16 v[230:231], v206 offset:128+4448
	s_waitcnt lgkmcnt(0)
	s_waitcnt lgkmcnt(0)
	s_nop 0
	v_mfma_f32_16x16x32_bf16 v[62:65], v[240:243], v[190:193], v[62:65]
	v_mfma_f32_16x16x32_bf16 v[66:69], v[236:239], v[190:193], v[66:69]
	v_mfma_f32_16x16x32_bf16 v[70:73], v[232:235], v[190:193], v[70:73]
	v_mfma_f32_16x16x32_bf16 v[78:81], v[228:231], v[190:193], v[78:81]
	s_cbranch_scc0 .LBB0_804
	v_mov_b32_e32 v232, v0
	v_mov_b32_e32 v185, v182
	s_branch .LBB0_800

; #define LAS __attribute__((address_space(3)))
; __device__ __forceinline__ void attn_tile_update(QTile& t, const int mq, int mk0, unsigned VSa, LAS unsigned char* KS, int lane) {
;     ...
;         const bf16x8 a0 = *(const LAS bf16x8*)(KS + ((fr)*HP + 32 * kk + 8 * fq) * 2);
;         const bf16x8 a1 = *(const LAS bf16x8*)(KS + ((16 + fr) * HP + 32 * kk + 8 * fq) * 2);
;         s0 = __builtin_amdgcn_mfma_f32_16x16x32_bf16(a0, t.q[kk], s0, 0, 0, 0);
;         s1 = __builtin_amdgcn_mfma_f32_16x16x32_bf16(a1, t.q[kk], s1, 0, 0, 0);
;     }
;     const float NEG = -__builtin_inff();
;     float mx = NEG;
;     bool v0[4], v1[4];
; #pragma unroll
;     for (int j = 0; j < 4; ++j) {
;         const int mk = mk0 + 4 * fq + j, jd = mq - mk;
;         v0[j] = (jd >= 0) && (jd <= 128) && (mk >= 0);
;         v1[j] = (jd - 16 >= 0) && (jd - 16 <= 128) && (mk + 16 >= 0);
;         if (v0[j]) mx = fmaxf(mx, s0[j]);
;         if (v1[j]) mx = fmaxf(mx, s1[j]);
;     }
;     mx = fmaxf(mx, __shfl_xor(mx, 16)); mx = fmaxf(mx, __shfl_xor(mx, 32));
.LBB0_809:
	ds_read_b128 v[150:153], v223
	ds_read_b128 v[154:157], v223 offset:64
	ds_read_b128 v[158:161], v223 offset:4352
	ds_read_b128 v[184:187], v223 offset:4416
	v_add_u32_e32 v0, s46, v147
	v_add_u32_e32 v149, 0x90, v0
	s_waitcnt lgkmcnt(3)
	v_mfma_f32_16x16x32_bf16 v[150:153], v[150:153], v[2:5], 0
	v_cmp_lt_i32_e32 vcc, -1, v146
	v_cmp_gt_u32_e64 s[6:7], s53, v149
	s_and_b64 vcc, vcc, s[6:7]
	s_waitcnt lgkmcnt(1)
	v_mfma_f32_16x16x32_bf16 v[158:161], v[158:161], v[2:5], 0
	v_cmp_lt_i32_e64 s[4:5], s52, v146
	v_cmp_lt_i32_e64 s[12:13], s56, v146
	v_cmp_lt_i32_e64 s[16:17], s57, v146
	v_mfma_f32_16x16x32_bf16 v[150:153], v[154:157], v[6:9], v[150:153]
	ds_read_b128 v[154:157], v223 offset:128
	ds_read_b128 v[188:191], v223 offset:192
	v_cmp_lt_i32_e64 s[20:21], s58, v146
	s_sub_i32 s46, s46, 32
	s_waitcnt lgkmcnt(2)
	v_mfma_f32_16x16x32_bf16 v[158:161], v[184:187], v[6:9], v[158:161]
	ds_read_b128 v[184:187], v223 offset:4480
	ds_read_b128 v[192:195], v223 offset:4544
	s_add_i32 s44, s44, 1
	v_add_u32_e32 v148, 32, v148
	s_waitcnt lgkmcnt(3)
	v_mfma_f32_16x16x32_bf16 v[150:153], v[154:157], v[10:13], v[150:153]
	v_add_u32_e32 v154, 0x80, v0
	v_cmp_gt_u32_e64 s[8:9], s53, v154
	s_and_b64 s[4:5], s[8:9], s[4:5]
	s_waitcnt lgkmcnt(1)
	v_mfma_f32_16x16x32_bf16 v[154:157], v[184:187], v[10:13], v[158:161]
	v_cmp_lt_i32_e64 s[8:9], -2, v146
	v_mfma_f32_16x16x32_bf16 v[150:153], v[188:191], v[14:17], v[150:153]
	s_waitcnt lgkmcnt(0)
	v_mfma_f32_16x16x32_bf16 v[154:157], v[192:195], v[14:17], v[154:157]
	s_nop 5
	v_max_f32_e32 v149, v150, v150
	v_max_f32_e32 v149, 0xff800000, v149
	v_cndmask_b32_e32 v149, v214, v149, vcc
	v_max_f32_e32 v158, v154, v154
	v_max_f32_e32 v158, v149, v158
	v_cndmask_b32_e64 v149, v149, v158, s[4:5]
	v_add_u32_e32 v158, 0x8f, v0
	v_cmp_gt_u32_e64 s[6:7], s53, v158
	v_add_u32_e32 v158, 0x7f, v0
	v_cmp_gt_u32_e64 s[10:11], s53, v158
	v_max_f32_e32 v158, v151, v151
	v_max_f32_e32 v158, v149, v158
	s_and_b64 s[6:7], s[8:9], s[6:7]
	v_cndmask_b32_e64 v149, v149, v158, s[6:7]
	v_max_f32_e32 v158, v155, v155
	v_max_f32_e32 v158, v149, v158
	s_and_b64 s[8:9], s[10:11], s[12:13]
	v_cndmask_b32_e64 v149, v149, v158, s[8:9]
	v_add_u32_e32 v158, 0x8e, v0
	v_cmp_gt_u32_e64 s[10:11], s53, v158
	v_add_u32_e32 v158, 0x7e, v0
	v_cmp_lt_i32_e64 s[12:13], -3, v146
	v_cmp_gt_u32_e64 s[14:15], s53, v158
	v_max_f32_e32 v158, v152, v152
	v_max_f32_e32 v158, v149, v158
	s_and_b64 s[10:11], s[12:13], s[10:11]
	v_cndmask_b32_e64 v149, v149, v158, s[10:11]
	v_max_f32_e32 v158, v149, v149
	v_max_f32_e32 v159, v156, v156
	v_max_f32_e32 v158, v158, v159
	s_and_b64 s[12:13], s[14:15], s[16:17]
	v_cndmask_b32_e64 v149, v149, v158, s[12:13]
	v_add_u32_e32 v158, 0x8d, v0
	v_add_u32_e32 v0, 0x7d, v0
	v_cmp_gt_u32_e64 s[14:15], s53, v158
	v_cmp_lt_i32_e64 s[16:17], -4, v146
	v_cmp_gt_u32_e64 s[18:19], s53, v0
	v_max_f32_e32 v0, v149, v149
	v_max_f32_e32 v158, v153, v153
	v_max_f32_e32 v0, v0, v158
	s_and_b64 s[14:15], s[16:17], s[14:15]
	v_cndmask_b32_e64 v0, v149, v0, s[14:15]
	v_max_f32_e32 v149, v0, v0
	v_max_f32_e32 v158, v157, v157
	v_max_f32_e32 v149, v149, v158
	s_and_b64 s[16:17], s[18:19], s[20:21]
	v_cndmask_b32_e64 v0, v0, v149, s[16:17]
	v_max_f32_e32 v0, v0, v0
	v_add_u32_e32 v146, 32, v146
	s_cmp_lt_u32 s44, 4
	v_mov_b32_e32 v149, v0
	s_waitcnt lgkmcnt(0)
; __device__ __forceinline__ bf16x8 pack8(f32x4 a, f32x4 b) { u32x4 w; w.x = pk2(a[0], a[1]); w.y = pk2(a[2], a[3]); w.z = pk2(b[0], b[1]); w.w = pk2(b[2], b[3]); return __builtin_bit_cast(bf16x8, w); }
; __device__ __forceinline__ void attn_tile_update(QTile& t, const int mq, int mk0, unsigned VSa, LAS unsigned char* KS, int lane) {
;     ...
;     mx = fmaxf(mx, __shfl_xor(mx, 16)); mx = fmaxf(mx, __shfl_xor(mx, 32));
;     const float mnew = fmaxf(t.m, mx);
;     const float muse = (mnew == NEG) ? 0.f : mnew;
;     const float alpha = __expf(t.m - muse);
;     f32x4 p0, p1; float ps = 0.f;
; #pragma unroll
;     for (int j = 0; j < 4; ++j) { p0[j] = v0[j] ? __expf(s0[j] - muse) : 0.f; p1[j] = v1[j] ? __expf(s1[j] - muse) : 0.f; ps += p0[j] + p1[j]; }
;     t.l = t.l * alpha + ps; t.m = mnew;
; #pragma unroll
;     for (int dt = 0; dt < 8; ++dt) t.o[dt] *= alpha;
;     const bf16x8 pf = pack8(p0, p1);
;     const unsigned vb = VSa + (unsigned)(((4 * fq + (fr >> 2)) * HP + 4 * (fr & 3)) * 2);
;     s16x4 ra[8], rb[8];
;     TR8(ra, vb, 0);
;     TR8(rb, vb, 128);
; #pragma unroll
;     for (int dt = 0; dt < 4; ++dt) t.o[dt] = __builtin_amdgcn_mfma_f32_16x16x32_bf16(cat8(ra[2 * dt], ra[2 * dt + 1]), pf, t.o[dt], 0, 0, 0);
; #pragma unroll
;     for (int dt = 0; dt < 4; ++dt) t.o[4 + dt] = __builtin_amdgcn_mfma_f32_16x16x32_bf16(cat8(rb[2 * dt], rb[2 * dt + 1]), pf, t.o[4 + dt], 0, 0, 0);
	s_nop 0
	v_permlane16_swap_b32_e32 v149, v0
	v_max_f32_e32 v0, v0, v149
	v_mov_b32_e32 v149, v0
	s_nop 1
	v_permlane32_swap_b32_e32 v149, v0
	v_max3_f32 v0, v227, v0, v149
	v_cmp_neq_f32_e64 s[18:19], s55, v0
	s_nop 1
	v_cndmask_b32_e64 v149, 0, v0, s[18:19]
	v_sub_f32_e32 v150, v150, v149
	v_sub_f32_e32 v154, v154, v149
	v_mul_f32_e32 v150, 0x3fb8aa3b, v150
	v_mul_f32_e32 v154, 0x3fb8aa3b, v154
	v_sub_f32_e32 v151, v151, v149
	v_sub_f32_e32 v155, v155, v149
	v_sub_f32_e32 v152, v152, v149
	v_sub_f32_e32 v156, v156, v149
	v_exp_f32_e32 v150, v150
	v_exp_f32_e32 v154, v154
	v_sub_f32_e32 v158, v227, v149
	v_mul_f32_e32 v151, 0x3fb8aa3b, v151
	v_mul_f32_e32 v155, 0x3fb8aa3b, v155
	v_mul_f32_e32 v152, 0x3fb8aa3b, v152
	v_mul_f32_e32 v156, 0x3fb8aa3b, v156
	v_sub_f32_e32 v153, v153, v149
	v_sub_f32_e32 v149, v157, v149
	v_exp_f32_e32 v151, v151
	v_exp_f32_e32 v155, v155
	v_exp_f32_e32 v152, v152
	v_exp_f32_e32 v156, v156
	v_mul_f32_e32 v153, 0x3fb8aa3b, v153
	v_mul_f32_e32 v149, 0x3fb8aa3b, v149
	v_mul_f32_e32 v158, 0x3fb8aa3b, v158
	v_exp_f32_e32 v153, v153
	v_exp_f32_e32 v149, v149
	v_exp_f32_e32 v192, v158
	v_cndmask_b32_e32 v150, 0, v150, vcc
	v_cndmask_b32_e64 v154, 0, v154, s[4:5]
	v_add_f32_e32 v159, v150, v154
	v_cndmask_b32_e64 v151, 0, v151, s[6:7]
	v_cndmask_b32_e64 v155, 0, v155, s[8:9]
	v_cndmask_b32_e64 v152, 0, v152, s[10:11]
	v_cndmask_b32_e64 v156, 0, v156, s[12:13]
	v_add_f32_e32 v159, 0, v159
	v_add_f32_e32 v160, v151, v155
	v_add_f32_e32 v193, v152, v156
	v_cndmask_b32_e64 v194, 0, v153, s[14:15]
	v_cndmask_b32_e64 v149, 0, v149, s[16:17]
	v_add_f32_e32 v181, v160, v159
	v_pk_mul_f32 v[36:37], v[36:37], v[192:193] op_sel_hi:[1,0]
	v_pk_mul_f32 v[34:35], v[34:35], v[192:193] op_sel_hi:[1,0]
	v_cvt_pk_bf16_f32 v150, v150, v151
	v_cvt_pk_bf16_f32 v151, v152, v194
	v_cvt_pk_bf16_f32 v152, v154, v155
	v_cvt_pk_bf16_f32 v153, v156, v149
	ds_read_b64_tr_b16 v[188:189], v206 offset:0+0
	ds_read_b64_tr_b16 v[190:191], v206 offset:0+4352
	ds_read_b64_tr_b16 v[184:185], v206 offset:0+32
	ds_read_b64_tr_b16 v[186:187], v206 offset:0+4384
	ds_read_b64_tr_b16 v[158:159], v206 offset:0+64
	ds_read_b64_tr_b16 v[160:161], v206 offset:0+4416
	ds_read_b64_tr_b16 v[154:155], v206 offset:0+96
	ds_read_b64_tr_b16 v[156:157], v206 offset:0+4448
	s_waitcnt lgkmcnt(0)
	v_pk_mul_f32 v[20:21], v[20:21], v[192:193] op_sel_hi:[1,0]
	v_pk_mul_f32 v[18:19], v[18:19], v[192:193] op_sel_hi:[1,0]
	v_pk_mul_f32 v[24:25], v[24:25], v[192:193] op_sel_hi:[1,0]
	v_pk_mul_f32 v[22:23], v[22:23], v[192:193] op_sel_hi:[1,0]
	v_pk_mul_f32 v[28:29], v[28:29], v[192:193] op_sel_hi:[1,0]
	v_pk_mul_f32 v[26:27], v[26:27], v[192:193] op_sel_hi:[1,0]
	v_pk_mul_f32 v[32:33], v[32:33], v[192:193] op_sel_hi:[1,0]
	v_pk_mul_f32 v[30:31], v[30:31], v[192:193] op_sel_hi:[1,0]
	v_pk_mul_f32 v[40:41], v[40:41], v[192:193] op_sel_hi:[1,0]
	v_pk_mul_f32 v[38:39], v[38:39], v[192:193] op_sel_hi:[1,0]
	v_pk_mul_f32 v[48:49], v[48:49], v[192:193] op_sel_hi:[1,0]
	v_pk_mul_f32 v[46:47], v[46:47], v[192:193] op_sel_hi:[1,0]
	v_pk_mul_f32 v[56:57], v[56:57], v[192:193] op_sel_hi:[1,0]
	v_pk_mul_f32 v[54:55], v[54:55], v[192:193] op_sel_hi:[1,0]
	v_mfma_f32_16x16x32_bf16 v[34:37], v[188:191], v[150:153], v[34:37]
	v_add_f32_e32 v181, v193, v181
	v_add_f32_e32 v149, v194, v149
	v_add_f32_e32 v149, v149, v181
	v_mfma_f32_16x16x32_bf16 v[18:21], v[184:187], v[150:153], v[18:21]
	v_fmac_f32_e32 v149, v183, v192
	v_mfma_f32_16x16x32_bf16 v[22:25], v[158:161], v[150:153], v[22:25]
	v_mfma_f32_16x16x32_bf16 v[26:29], v[154:157], v[150:153], v[26:29]
	ds_read_b64_tr_b16 v[188:189], v206 offset:128+0
	ds_read_b64_tr_b16 v[190:191], v206 offset:128+4352
	ds_read_b64_tr_b16 v[184:185], v206 offset:128+32
	ds_read_b64_tr_b16 v[186:187], v206 offset:128+4384
	ds_read_b64_tr_b16 v[158:159], v206 offset:128+64
	ds_read_b64_tr_b16 v[160:161], v206 offset:128+4416
	ds_read_b64_tr_b16 v[154:155], v206 offset:128+96
	ds_read_b64_tr_b16 v[156:157], v206 offset:128+4448
	s_waitcnt lgkmcnt(0)
	s_waitcnt lgkmcnt(0)
	s_nop 0
	v_mfma_f32_16x16x32_bf16 v[30:33], v[188:191], v[150:153], v[30:33]
	v_mfma_f32_16x16x32_bf16 v[38:41], v[184:187], v[150:153], v[38:41]
	v_mfma_f32_16x16x32_bf16 v[46:49], v[158:161], v[150:153], v[46:49]
	v_mfma_f32_16x16x32_bf16 v[54:57], v[154:157], v[150:153], v[54:57]
	s_cbranch_scc0 .LBB0_778
	v_mov_b32_e32 v227, v0
	v_mov_b32_e32 v183, v149
	s_branch .LBB0_807
